# in-proj: weight rows permuted at transpose so bj halves are adjacent; epilogue stores 8 rows x 128B via DPP row_ror exchange
# speedup vs baseline: 1.0005x; 1.0005x over previous
; __device__ __forceinline__ unsigned cvtpk(float lo, float hi) { f32x2 v = {lo, hi}; bf16x2_t b = __builtin_convertvector(v, bf16x2_t); return __builtin_bit_cast(unsigned, b); }
;     __device__ __forceinline__ void operator()(const f32x4 (&acc)[2][2][4][2], const Unit& u, int wr, int wc, int fr, int fq, const float (&pv)[8]) const {
;         const int row0 = u.pm * BM + wr * 64 + fr, col0 = u.pn * BM + wc * 32 + 8 * fq;
;         const float sc = (u.pn >= t0 && u.pn < t1) ? tscale : 1.f;
; #pragma unroll
;         for (int ai = 0; ai < 2; ++ai)
; #pragma unroll
;             for (int m = 0; m < 4; ++m) { const int row = row0 + ai * HALF + m * 16; const float rs = __builtin_amdgcn_rsqf(pv[ai * 4 + m] * (1.f / DM) + EPS) * sc;
;                 bf16_t* rowp = O + (size_t)row * ldc + col0;
; #pragma unroll
;                 for (int bj = 0; bj < 2; ++bj) { const f32x4 v0 = acc[ai][bj][m][0] * rs, v1 = acc[ai][bj][m][1] * rs;
;                     u32x4 w; w.x = cvtpk(v0[0], v0[1]); w.y = cvtpk(v0[2], v0[3]); w.z = cvtpk(v1[0], v1[1]); w.w = cvtpk(v1[2], v1[3]);
;                     *(u32x4*)(rowp + bj * HALF) = w; } }
;     }
.LBB0_293:
	s_cmp_ge_i32 s48, s33
	s_waitcnt vmcnt(8)
	s_cselect_b64 s[2:3], -1, 0
	s_cmp_lt_i32 s48, s42
	v_and_b32_e32 v141, 8, v223
	s_cselect_b64 s[10:11], -1, 0
	s_and_b64 vcc, s[2:3], s[10:11]
	v_and_b32_e32 v142, 0x60, v146
	v_sub_u32_e32 v184, v140, v141
	v_add_u32_e32 v142, v142, v146
	v_cndmask_b32_e32 v157, 1.0, v228, vcc
	v_lshl_add_u32 v142, v141, 2, v142
	v_cmp_ne_u32_e64 s[10:11], 0, v141
	v_lshl_or_b32 v142, s48, 8, v142
	s_lshl_b32 s2, s44, 4
	v_ashrrev_i32_e32 v143, 31, v142
	s_add_i32 s2, s2, 64
	v_lshlrev_b32_e32 v250, 4, v141
	v_mov_b32_e32 v251, 0
	v_sub_u32_e32 v250, s2, v250
	v_lshlrev_b64 v[142:143], 1, v[142:143]
	v_fmamk_f32 v141, v148, 0x3a800000, v222
	v_rsq_f32_e32 v141, v141
	v_mad_i64_i32 v[158:159], vcc, s44, v184, 0
	v_mul_f32_e32 v156, v157, v141
	v_pk_mul_f32 v[126:127], v[156:157], v[126:127] op_sel_hi:[0,1]
	v_pk_mul_f32 v[128:129], v[156:157], v[128:129] op_sel_hi:[0,1]
	v_pk_mul_f32 v[122:123], v[156:157], v[122:123] op_sel_hi:[0,1]
	v_pk_mul_f32 v[124:125], v[156:157], v[124:125] op_sel_hi:[0,1]
	v_pk_mul_f32 v[118:119], v[156:157], v[118:119] op_sel_hi:[0,1]
	v_pk_mul_f32 v[120:121], v[156:157], v[120:121] op_sel_hi:[0,1]
	v_pk_mul_f32 v[110:111], v[156:157], v[110:111] op_sel_hi:[0,1]
	v_pk_mul_f32 v[112:113], v[156:157], v[112:113] op_sel_hi:[0,1]
	v_lshl_add_u64 v[158:159], v[158:159], 1, s[14:15]
	v_cvt_pk_bf16_f32 v118, v118, v119
	v_cvt_pk_bf16_f32 v119, v120, v121
	v_cvt_pk_bf16_f32 v120, v110, v111
	v_cvt_pk_bf16_f32 v121, v112, v113
	v_cvt_pk_bf16_f32 v126, v126, v127
	v_cvt_pk_bf16_f32 v127, v128, v129
	v_cvt_pk_bf16_f32 v128, v122, v123
	v_cvt_pk_bf16_f32 v129, v124, v125
	v_lshl_add_u64 v[158:159], v[158:159], 0, v[142:143]
	v_mov_b32_dpp v122, v118 row_ror:8 row_mask:0xf bank_mask:0xf
	v_mov_b32_dpp v123, v119 row_ror:8 row_mask:0xf bank_mask:0xf
	v_mov_b32_dpp v124, v120 row_ror:8 row_mask:0xf bank_mask:0xf
	v_mov_b32_dpp v125, v121 row_ror:8 row_mask:0xf bank_mask:0xf
	v_lshl_add_u64 v[160:161], v[158:159], 0, v[250:251]
	v_cndmask_b32_e64 v110, v126, v122, s[10:11]
	v_cndmask_b32_e64 v111, v127, v123, s[10:11]
	v_cndmask_b32_e64 v112, v128, v124, s[10:11]
	v_cndmask_b32_e64 v113, v129, v125, s[10:11]
	v_cndmask_b32_e64 v122, v122, v126, s[10:11]
	v_cndmask_b32_e64 v123, v123, v127, s[10:11]
	v_cndmask_b32_e64 v124, v124, v128, s[10:11]
	v_cndmask_b32_e64 v125, v125, v129, s[10:11]
	global_store_dwordx4 v[158:159], v[110:113], off
	global_store_dwordx4 v[160:161], v[122:125], off
	v_fmamk_f32 v141, v149, 0x3a800000, v222
	v_rsq_f32_e32 v141, v141
	v_add_u32_e32 v185, 0x10, v184
	v_mad_i64_i32 v[158:159], vcc, s44, v185, 0
	v_mul_f32_e32 v156, v157, v141
	v_pk_mul_f32 v[114:115], v[156:157], v[114:115] op_sel_hi:[0,1]
	v_pk_mul_f32 v[116:117], v[156:157], v[116:117] op_sel_hi:[0,1]
	v_pk_mul_f32 v[106:107], v[156:157], v[106:107] op_sel_hi:[0,1]
	v_pk_mul_f32 v[108:109], v[156:157], v[108:109] op_sel_hi:[0,1]
	v_pk_mul_f32 v[102:103], v[156:157], v[102:103] op_sel_hi:[0,1]
	v_pk_mul_f32 v[104:105], v[156:157], v[104:105] op_sel_hi:[0,1]
	v_pk_mul_f32 v[94:95], v[156:157], v[94:95] op_sel_hi:[0,1]
	v_pk_mul_f32 v[96:97], v[156:157], v[96:97] op_sel_hi:[0,1]
	v_lshl_add_u64 v[158:159], v[158:159], 1, s[14:15]
	v_cvt_pk_bf16_f32 v102, v102, v103
	v_cvt_pk_bf16_f32 v103, v104, v105
	v_cvt_pk_bf16_f32 v104, v94, v95
	v_cvt_pk_bf16_f32 v105, v96, v97
	v_cvt_pk_bf16_f32 v114, v114, v115
	v_cvt_pk_bf16_f32 v115, v116, v117
	v_cvt_pk_bf16_f32 v116, v106, v107
	v_cvt_pk_bf16_f32 v117, v108, v109
	v_lshl_add_u64 v[158:159], v[158:159], 0, v[142:143]
	v_mov_b32_dpp v106, v102 row_ror:8 row_mask:0xf bank_mask:0xf
	v_mov_b32_dpp v107, v103 row_ror:8 row_mask:0xf bank_mask:0xf
	v_mov_b32_dpp v108, v104 row_ror:8 row_mask:0xf bank_mask:0xf
	v_mov_b32_dpp v109, v105 row_ror:8 row_mask:0xf bank_mask:0xf
	v_lshl_add_u64 v[160:161], v[158:159], 0, v[250:251]
	v_cndmask_b32_e64 v94, v114, v106, s[10:11]
	v_cndmask_b32_e64 v95, v115, v107, s[10:11]
	v_cndmask_b32_e64 v96, v116, v108, s[10:11]
	v_cndmask_b32_e64 v97, v117, v109, s[10:11]
	v_cndmask_b32_e64 v106, v106, v114, s[10:11]
	v_cndmask_b32_e64 v107, v107, v115, s[10:11]
	v_cndmask_b32_e64 v108, v108, v116, s[10:11]
	v_cndmask_b32_e64 v109, v109, v117, s[10:11]
	global_store_dwordx4 v[158:159], v[94:97], off
	global_store_dwordx4 v[160:161], v[106:109], off
	v_fmamk_f32 v141, v150, 0x3a800000, v222
	v_rsq_f32_e32 v141, v141
	v_add_u32_e32 v185, 0x20, v184
	v_mad_i64_i32 v[158:159], vcc, s44, v185, 0
	v_mul_f32_e32 v156, v157, v141
	v_pk_mul_f32 v[98:99], v[156:157], v[98:99] op_sel_hi:[0,1]
	v_pk_mul_f32 v[100:101], v[156:157], v[100:101] op_sel_hi:[0,1]
	v_pk_mul_f32 v[90:91], v[156:157], v[90:91] op_sel_hi:[0,1]
	v_pk_mul_f32 v[92:93], v[156:157], v[92:93] op_sel_hi:[0,1]
	v_pk_mul_f32 v[86:87], v[156:157], v[86:87] op_sel_hi:[0,1]
	v_pk_mul_f32 v[88:89], v[156:157], v[88:89] op_sel_hi:[0,1]
	v_pk_mul_f32 v[78:79], v[156:157], v[78:79] op_sel_hi:[0,1]
	v_pk_mul_f32 v[80:81], v[156:157], v[80:81] op_sel_hi:[0,1]
	v_lshl_add_u64 v[158:159], v[158:159], 1, s[14:15]
	v_cvt_pk_bf16_f32 v86, v86, v87
	v_cvt_pk_bf16_f32 v87, v88, v89
	v_cvt_pk_bf16_f32 v88, v78, v79
	v_cvt_pk_bf16_f32 v89, v80, v81
	v_cvt_pk_bf16_f32 v98, v98, v99
	v_cvt_pk_bf16_f32 v99, v100, v101
	v_cvt_pk_bf16_f32 v100, v90, v91
	v_cvt_pk_bf16_f32 v101, v92, v93
	v_lshl_add_u64 v[158:159], v[158:159], 0, v[142:143]
	v_mov_b32_dpp v90, v86 row_ror:8 row_mask:0xf bank_mask:0xf
	v_mov_b32_dpp v91, v87 row_ror:8 row_mask:0xf bank_mask:0xf
	v_mov_b32_dpp v92, v88 row_ror:8 row_mask:0xf bank_mask:0xf
	v_mov_b32_dpp v93, v89 row_ror:8 row_mask:0xf bank_mask:0xf
; __device__ __forceinline__ unsigned cvtpk(float lo, float hi) { f32x2 v = {lo, hi}; bf16x2_t b = __builtin_convertvector(v, bf16x2_t); return __builtin_bit_cast(unsigned, b); }
;     __device__ __forceinline__ void operator()(const f32x4 (&acc)[2][2][4][2], const Unit& u, int wr, int wc, int fr, int fq, const float (&pv)[8]) const {
;     ...
;             for (int m = 0; m < 4; ++m) { const int row = row0 + ai * HALF + m * 16; const float rs = __builtin_amdgcn_rsqf(pv[ai * 4 + m] * (1.f / DM) + EPS) * sc;
;                 bf16_t* rowp = O + (size_t)row * ldc + col0;
; #pragma unroll
;                 for (int bj = 0; bj < 2; ++bj) { const f32x4 v0 = acc[ai][bj][m][0] * rs, v1 = acc[ai][bj][m][1] * rs;
;                     u32x4 w; w.x = cvtpk(v0[0], v0[1]); w.y = cvtpk(v0[2], v0[3]); w.z = cvtpk(v1[0], v1[1]); w.w = cvtpk(v1[2], v1[3]);
;                     *(u32x4*)(rowp + bj * HALF) = w; } }
	v_lshl_add_u64 v[160:161], v[158:159], 0, v[250:251]
	v_cndmask_b32_e64 v78, v98, v90, s[10:11]
	v_cndmask_b32_e64 v79, v99, v91, s[10:11]
	v_cndmask_b32_e64 v80, v100, v92, s[10:11]
	v_cndmask_b32_e64 v81, v101, v93, s[10:11]
	v_cndmask_b32_e64 v90, v90, v98, s[10:11]
	v_cndmask_b32_e64 v91, v91, v99, s[10:11]
	v_cndmask_b32_e64 v92, v92, v100, s[10:11]
	v_cndmask_b32_e64 v93, v93, v101, s[10:11]
	global_store_dwordx4 v[158:159], v[78:81], off
	global_store_dwordx4 v[160:161], v[90:93], off
	v_fmamk_f32 v141, v151, 0x3a800000, v222
	v_rsq_f32_e32 v141, v141
	v_add_u32_e32 v185, 0x30, v184
	v_mad_i64_i32 v[158:159], vcc, s44, v185, 0
	v_mul_f32_e32 v156, v157, v141
	v_pk_mul_f32 v[82:83], v[156:157], v[82:83] op_sel_hi:[0,1]
	v_pk_mul_f32 v[84:85], v[156:157], v[84:85] op_sel_hi:[0,1]
	v_pk_mul_f32 v[74:75], v[156:157], v[74:75] op_sel_hi:[0,1]
	v_pk_mul_f32 v[76:77], v[156:157], v[76:77] op_sel_hi:[0,1]
	v_pk_mul_f32 v[70:71], v[156:157], v[70:71] op_sel_hi:[0,1]
	v_pk_mul_f32 v[72:73], v[156:157], v[72:73] op_sel_hi:[0,1]
	v_pk_mul_f32 v[66:67], v[156:157], v[66:67] op_sel_hi:[0,1]
	v_pk_mul_f32 v[68:69], v[156:157], v[68:69] op_sel_hi:[0,1]
	v_lshl_add_u64 v[158:159], v[158:159], 1, s[14:15]
	v_cvt_pk_bf16_f32 v70, v70, v71
	v_cvt_pk_bf16_f32 v71, v72, v73
	v_cvt_pk_bf16_f32 v72, v66, v67
	v_cvt_pk_bf16_f32 v73, v68, v69
	v_cvt_pk_bf16_f32 v82, v82, v83
	v_cvt_pk_bf16_f32 v83, v84, v85
	v_cvt_pk_bf16_f32 v84, v74, v75
	v_cvt_pk_bf16_f32 v85, v76, v77
	v_lshl_add_u64 v[158:159], v[158:159], 0, v[142:143]
	v_mov_b32_dpp v74, v70 row_ror:8 row_mask:0xf bank_mask:0xf
	v_mov_b32_dpp v75, v71 row_ror:8 row_mask:0xf bank_mask:0xf
	v_mov_b32_dpp v76, v72 row_ror:8 row_mask:0xf bank_mask:0xf
	v_mov_b32_dpp v77, v73 row_ror:8 row_mask:0xf bank_mask:0xf
	v_lshl_add_u64 v[160:161], v[158:159], 0, v[250:251]
	v_cndmask_b32_e64 v66, v82, v74, s[10:11]
	v_cndmask_b32_e64 v67, v83, v75, s[10:11]
	v_cndmask_b32_e64 v68, v84, v76, s[10:11]
	v_cndmask_b32_e64 v69, v85, v77, s[10:11]
	v_cndmask_b32_e64 v74, v74, v82, s[10:11]
	v_cndmask_b32_e64 v75, v75, v83, s[10:11]
	v_cndmask_b32_e64 v76, v76, v84, s[10:11]
	v_cndmask_b32_e64 v77, v77, v85, s[10:11]
	global_store_dwordx4 v[158:159], v[66:69], off
	global_store_dwordx4 v[160:161], v[74:77], off
	v_fmamk_f32 v141, v152, 0x3a800000, v222
	v_rsq_f32_e32 v141, v141
	v_add_u32_e32 v185, 0x80, v184
	v_mad_i64_i32 v[158:159], vcc, s44, v185, 0
	v_mul_f32_e32 v156, v157, v141
	v_pk_mul_f32 v[62:63], v[156:157], v[62:63] op_sel_hi:[0,1]
	v_pk_mul_f32 v[64:65], v[156:157], v[64:65] op_sel_hi:[0,1]
	v_pk_mul_f32 v[58:59], v[156:157], v[58:59] op_sel_hi:[0,1]
	v_pk_mul_f32 v[60:61], v[156:157], v[60:61] op_sel_hi:[0,1]
	v_pk_mul_f32 v[54:55], v[156:157], v[54:55] op_sel_hi:[0,1]
	v_pk_mul_f32 v[56:57], v[156:157], v[56:57] op_sel_hi:[0,1]
	v_pk_mul_f32 v[46:47], v[156:157], v[46:47] op_sel_hi:[0,1]
	v_pk_mul_f32 v[48:49], v[156:157], v[48:49] op_sel_hi:[0,1]
	v_lshl_add_u64 v[158:159], v[158:159], 1, s[14:15]
	v_cvt_pk_bf16_f32 v54, v54, v55
	v_cvt_pk_bf16_f32 v55, v56, v57
	v_cvt_pk_bf16_f32 v56, v46, v47
	v_cvt_pk_bf16_f32 v57, v48, v49
	v_cvt_pk_bf16_f32 v62, v62, v63
	v_cvt_pk_bf16_f32 v63, v64, v65
	v_cvt_pk_bf16_f32 v64, v58, v59
	v_cvt_pk_bf16_f32 v65, v60, v61
	v_lshl_add_u64 v[158:159], v[158:159], 0, v[142:143]
	v_mov_b32_dpp v58, v54 row_ror:8 row_mask:0xf bank_mask:0xf
	v_mov_b32_dpp v59, v55 row_ror:8 row_mask:0xf bank_mask:0xf
	v_mov_b32_dpp v60, v56 row_ror:8 row_mask:0xf bank_mask:0xf
	v_mov_b32_dpp v61, v57 row_ror:8 row_mask:0xf bank_mask:0xf
	v_lshl_add_u64 v[160:161], v[158:159], 0, v[250:251]
	v_cndmask_b32_e64 v46, v62, v58, s[10:11]
	v_cndmask_b32_e64 v47, v63, v59, s[10:11]
	v_cndmask_b32_e64 v48, v64, v60, s[10:11]
	v_cndmask_b32_e64 v49, v65, v61, s[10:11]
	v_cndmask_b32_e64 v58, v58, v62, s[10:11]
	v_cndmask_b32_e64 v59, v59, v63, s[10:11]
	v_cndmask_b32_e64 v60, v60, v64, s[10:11]
	v_cndmask_b32_e64 v61, v61, v65, s[10:11]
	global_store_dwordx4 v[158:159], v[46:49], off
	global_store_dwordx4 v[160:161], v[58:61], off
	v_fmamk_f32 v141, v153, 0x3a800000, v222
	v_rsq_f32_e32 v141, v141
	v_add_u32_e32 v185, 0x90, v184
	v_mad_i64_i32 v[158:159], vcc, s44, v185, 0
	v_mul_f32_e32 v156, v157, v141
	v_pk_mul_f32 v[50:51], v[156:157], v[50:51] op_sel_hi:[0,1]
	v_pk_mul_f32 v[52:53], v[156:157], v[52:53] op_sel_hi:[0,1]
	v_pk_mul_f32 v[42:43], v[156:157], v[42:43] op_sel_hi:[0,1]
	v_pk_mul_f32 v[44:45], v[156:157], v[44:45] op_sel_hi:[0,1]
	v_pk_mul_f32 v[38:39], v[156:157], v[38:39] op_sel_hi:[0,1]
	v_pk_mul_f32 v[40:41], v[156:157], v[40:41] op_sel_hi:[0,1]
	v_pk_mul_f32 v[30:31], v[156:157], v[30:31] op_sel_hi:[0,1]
	v_pk_mul_f32 v[32:33], v[156:157], v[32:33] op_sel_hi:[0,1]
	v_lshl_add_u64 v[158:159], v[158:159], 1, s[14:15]
; __device__ __forceinline__ unsigned cvtpk(float lo, float hi) { f32x2 v = {lo, hi}; bf16x2_t b = __builtin_convertvector(v, bf16x2_t); return __builtin_bit_cast(unsigned, b); }
; #define PG8_BAR __builtin_amdgcn_s_barrier()
;     __device__ __forceinline__ void operator()(const f32x4 (&acc)[2][2][4][2], const Unit& u, int wr, int wc, int fr, int fq, const float (&pv)[8]) const {
;     ...
;             for (int m = 0; m < 4; ++m) { const int row = row0 + ai * HALF + m * 16; const float rs = __builtin_amdgcn_rsqf(pv[ai * 4 + m] * (1.f / DM) + EPS) * sc;
;                 bf16_t* rowp = O + (size_t)row * ldc + col0;
; #pragma unroll
;                 for (int bj = 0; bj < 2; ++bj) { const f32x4 v0 = acc[ai][bj][m][0] * rs, v1 = acc[ai][bj][m][1] * rs;
;                     u32x4 w; w.x = cvtpk(v0[0], v0[1]); w.y = cvtpk(v0[2], v0[3]); w.z = cvtpk(v1[0], v1[1]); w.w = cvtpk(v1[2], v1[3]);
;                     *(u32x4*)(rowp + bj * HALF) = w; } }
;     }
; template <class Epi>
; __device__ __forceinline__ void gemm_phase(LAS unsigned char* lds, const Gemm g, const StaticOrder& S, const Epi& E, const int wave_id) {
;     ...
;         if (!has_next) break;
; #pragma unroll
;         for (int a = 0; a < 2; ++a)
; #pragma unroll
;             for (int b = 0; b < 2; ++b)
; #pragma unroll
;                 for (int m = 0; m < 4; ++m)
; #pragma unroll
;                     for (int n = 0; n < 2; ++n) acc[a][b][m][n] = (f32x4){0.f, 0.f, 0.f, 0.f};
;         cur = nxt; cA = nA; cB = nB; ++ui;
;         if (wr == 1) PG8_BAR;
;     }
	v_cvt_pk_bf16_f32 v38, v38, v39
	v_cvt_pk_bf16_f32 v39, v40, v41
	v_cvt_pk_bf16_f32 v40, v30, v31
	v_cvt_pk_bf16_f32 v41, v32, v33
	v_cvt_pk_bf16_f32 v50, v50, v51
	v_cvt_pk_bf16_f32 v51, v52, v53
	v_cvt_pk_bf16_f32 v52, v42, v43
	v_cvt_pk_bf16_f32 v53, v44, v45
	v_lshl_add_u64 v[158:159], v[158:159], 0, v[142:143]
	v_mov_b32_dpp v42, v38 row_ror:8 row_mask:0xf bank_mask:0xf
	v_mov_b32_dpp v43, v39 row_ror:8 row_mask:0xf bank_mask:0xf
	v_mov_b32_dpp v44, v40 row_ror:8 row_mask:0xf bank_mask:0xf
	v_mov_b32_dpp v45, v41 row_ror:8 row_mask:0xf bank_mask:0xf
	v_lshl_add_u64 v[160:161], v[158:159], 0, v[250:251]
	v_cndmask_b32_e64 v30, v50, v42, s[10:11]
	v_cndmask_b32_e64 v31, v51, v43, s[10:11]
	v_cndmask_b32_e64 v32, v52, v44, s[10:11]
	v_cndmask_b32_e64 v33, v53, v45, s[10:11]
	v_cndmask_b32_e64 v42, v42, v50, s[10:11]
	v_cndmask_b32_e64 v43, v43, v51, s[10:11]
	v_cndmask_b32_e64 v44, v44, v52, s[10:11]
	v_cndmask_b32_e64 v45, v45, v53, s[10:11]
	global_store_dwordx4 v[158:159], v[30:33], off
	global_store_dwordx4 v[160:161], v[42:45], off
	v_fmamk_f32 v141, v154, 0x3a800000, v222
	v_rsq_f32_e32 v141, v141
	v_add_u32_e32 v185, 0xa0, v184
	v_mad_i64_i32 v[158:159], vcc, s44, v185, 0
	v_mul_f32_e32 v156, v157, v141
	v_pk_mul_f32 v[34:35], v[156:157], v[34:35] op_sel_hi:[0,1]
	v_pk_mul_f32 v[36:37], v[156:157], v[36:37] op_sel_hi:[0,1]
	v_pk_mul_f32 v[26:27], v[156:157], v[26:27] op_sel_hi:[0,1]
	v_pk_mul_f32 v[28:29], v[156:157], v[28:29] op_sel_hi:[0,1]
	v_pk_mul_f32 v[22:23], v[156:157], v[22:23] op_sel_hi:[0,1]
	v_pk_mul_f32 v[24:25], v[156:157], v[24:25] op_sel_hi:[0,1]
	v_pk_mul_f32 v[14:15], v[156:157], v[14:15] op_sel_hi:[0,1]
	v_pk_mul_f32 v[16:17], v[156:157], v[16:17] op_sel_hi:[0,1]
	v_lshl_add_u64 v[158:159], v[158:159], 1, s[14:15]
	v_cvt_pk_bf16_f32 v22, v22, v23
	v_cvt_pk_bf16_f32 v23, v24, v25
	v_cvt_pk_bf16_f32 v24, v14, v15
	v_cvt_pk_bf16_f32 v25, v16, v17
	v_cvt_pk_bf16_f32 v34, v34, v35
	v_cvt_pk_bf16_f32 v35, v36, v37
	v_cvt_pk_bf16_f32 v36, v26, v27
	v_cvt_pk_bf16_f32 v37, v28, v29
	v_lshl_add_u64 v[158:159], v[158:159], 0, v[142:143]
	v_mov_b32_dpp v26, v22 row_ror:8 row_mask:0xf bank_mask:0xf
	v_mov_b32_dpp v27, v23 row_ror:8 row_mask:0xf bank_mask:0xf
	v_mov_b32_dpp v28, v24 row_ror:8 row_mask:0xf bank_mask:0xf
	v_mov_b32_dpp v29, v25 row_ror:8 row_mask:0xf bank_mask:0xf
	v_lshl_add_u64 v[160:161], v[158:159], 0, v[250:251]
	v_cndmask_b32_e64 v14, v34, v26, s[10:11]
	v_cndmask_b32_e64 v15, v35, v27, s[10:11]
	v_cndmask_b32_e64 v16, v36, v28, s[10:11]
	v_cndmask_b32_e64 v17, v37, v29, s[10:11]
	v_cndmask_b32_e64 v26, v26, v34, s[10:11]
	v_cndmask_b32_e64 v27, v27, v35, s[10:11]
	v_cndmask_b32_e64 v28, v28, v36, s[10:11]
	v_cndmask_b32_e64 v29, v29, v37, s[10:11]
	global_store_dwordx4 v[158:159], v[14:17], off
	global_store_dwordx4 v[160:161], v[26:29], off
	v_fmamk_f32 v141, v155, 0x3a800000, v222
	v_rsq_f32_e32 v141, v141
	v_add_u32_e32 v185, 0xb0, v184
	v_mad_i64_i32 v[158:159], vcc, s44, v185, 0
	v_mul_f32_e32 v156, v157, v141
	v_pk_mul_f32 v[18:19], v[156:157], v[18:19] op_sel_hi:[0,1]
	v_pk_mul_f32 v[20:21], v[156:157], v[20:21] op_sel_hi:[0,1]
	v_pk_mul_f32 v[10:11], v[156:157], v[10:11] op_sel_hi:[0,1]
	v_pk_mul_f32 v[12:13], v[156:157], v[12:13] op_sel_hi:[0,1]
	v_pk_mul_f32 v[6:7], v[156:157], v[6:7] op_sel_hi:[0,1]
	v_pk_mul_f32 v[8:9], v[156:157], v[8:9] op_sel_hi:[0,1]
	v_pk_mul_f32 v[2:3], v[156:157], v[2:3] op_sel_hi:[0,1]
	v_pk_mul_f32 v[4:5], v[156:157], v[4:5] op_sel_hi:[0,1]
	v_lshl_add_u64 v[158:159], v[158:159], 1, s[14:15]
	v_cvt_pk_bf16_f32 v6, v6, v7
	v_cvt_pk_bf16_f32 v7, v8, v9
	v_cvt_pk_bf16_f32 v8, v2, v3
	v_cvt_pk_bf16_f32 v9, v4, v5
	v_cvt_pk_bf16_f32 v18, v18, v19
	v_cvt_pk_bf16_f32 v19, v20, v21
	v_cvt_pk_bf16_f32 v20, v10, v11
	v_cvt_pk_bf16_f32 v21, v12, v13
	v_lshl_add_u64 v[158:159], v[158:159], 0, v[142:143]
	v_mov_b32_dpp v10, v6 row_ror:8 row_mask:0xf bank_mask:0xf
	v_mov_b32_dpp v11, v7 row_ror:8 row_mask:0xf bank_mask:0xf
	v_mov_b32_dpp v12, v8 row_ror:8 row_mask:0xf bank_mask:0xf
	v_mov_b32_dpp v13, v9 row_ror:8 row_mask:0xf bank_mask:0xf
	v_lshl_add_u64 v[160:161], v[158:159], 0, v[250:251]
	v_cndmask_b32_e64 v2, v18, v10, s[10:11]
	v_cndmask_b32_e64 v3, v19, v11, s[10:11]
	v_cndmask_b32_e64 v4, v20, v12, s[10:11]
	v_cndmask_b32_e64 v5, v21, v13, s[10:11]
	v_cndmask_b32_e64 v10, v10, v18, s[10:11]
	v_cndmask_b32_e64 v11, v11, v19, s[10:11]
	v_cndmask_b32_e64 v12, v12, v20, s[10:11]
	v_cndmask_b32_e64 v13, v13, v21, s[10:11]
	global_store_dwordx4 v[158:159], v[2:5], off
	global_store_dwordx4 v[160:161], v[10:13], off
	s_andn2_b64 vcc, exec, s[40:41]
	s_mov_b64 s[2:3], -1
	s_cbranch_vccnz .LBB0_284
	s_andn2_b64 vcc, exec, s[18:19]
	s_cbranch_vccnz .LBB0_283
	s_barrier
	s_branch .LBB0_283

; #define LAS __attribute__((address_space(3)))
; __device__ __forceinline__ unsigned cvtpk(float lo, float hi) { f32x2 v = {lo, hi}; bf16x2_t b = __builtin_convertvector(v, bf16x2_t); return __builtin_bit_cast(unsigned, b); }
; __device__ __forceinline__ void transpose_item(const float* W, int K, int N, bf16_t* WT, const float* gain, int mode, LAS float* scr, int item, int lane) {
;     ...
;     const int nblk = N / 32, kb = item / nblk, nb = item % nblk, k0 = 64 * kb, n0 = 32 * nb;
; #pragma unroll 8
;     for (int i = 0; i < 32; ++i) { const int kk = 2 * i + (lane >> 5); float w = __builtin_nontemporal_load(W + (size_t)(k0 + kk) * N + n0 + (lane & 31)); if (gain) w *= gain[k0 + kk]; scr[kk * 33 + (lane & 31)] = w; }
;     int d0 = n0;
;     if (mode == 1) { const int j = n0 < DFF ? n0 : n0 - DFF; d0 = 256 * (j >> 7) + (j & 127) + (n0 < DFF ? 0 : 128); }
;     const int c = lane & 7;
; #pragma unroll
;     for (int j = 0; j < 4; ++j) { const int n = (lane >> 3) + 8 * j; const LAS float* s = scr + (8 * c) * 33 + n;
;         u32x4 o; o.x = cvtpk(s[0 * 33], s[1 * 33]); o.y = cvtpk(s[2 * 33], s[3 * 33]); o.z = cvtpk(s[4 * 33], s[5 * 33]); o.w = cvtpk(s[6 * 33], s[7 * 33]);
;         *(u32x4*)(WT + (size_t)(d0 + n) * K + k0 + 8 * c) = o; }
.LBB0_352:
	v_lshl_add_u64 v[36:37], v[30:31], 0, v[0:1]
	v_lshl_add_u64 v[38:39], v[32:33], 0, s[10:11]
	v_lshl_add_u64 v[40:41], v[28:29], 0, v[0:1]
	v_lshl_add_u64 v[42:43], v[26:27], 0, s[10:11]
	v_lshl_add_u64 v[44:45], v[24:25], 0, v[0:1]
	v_lshl_add_u64 v[46:47], v[22:23], 0, s[10:11]
	v_lshl_add_u64 v[48:49], v[20:21], 0, v[0:1]
	v_lshl_add_u64 v[50:51], v[18:19], 0, s[10:11]
	v_lshl_add_u64 v[52:53], v[16:17], 0, v[0:1]
	v_lshl_add_u64 v[54:55], v[14:15], 0, s[10:11]
	v_lshl_add_u64 v[56:57], v[12:13], 0, v[0:1]
	v_lshl_add_u64 v[58:59], v[10:11], 0, s[10:11]
	v_lshl_add_u64 v[60:61], v[8:9], 0, v[0:1]
	v_lshl_add_u64 v[62:63], v[6:7], 0, s[10:11]
	v_lshl_add_u64 v[64:65], v[4:5], 0, v[0:1]
	v_lshl_add_u64 v[66:67], v[2:3], 0, s[10:11]
	global_load_dword v36, v[36:37], off nt
	s_nop 0
	global_load_dword v37, v[38:39], off
	s_nop 0
	global_load_dword v38, v[40:41], off nt
	global_load_dword v39, v[42:43], off
	s_nop 0
	global_load_dword v40, v[44:45], off nt
	global_load_dword v41, v[46:47], off
	global_load_dword v42, v[48:49], off nt
	global_load_dword v43, v[50:51], off
	s_nop 0
	global_load_dword v44, v[52:53], off nt
	global_load_dword v45, v[54:55], off
	global_load_dword v46, v[56:57], off nt
	global_load_dword v47, v[58:59], off
	global_load_dword v48, v[60:61], off nt
	global_load_dword v49, v[62:63], off
	global_load_dword v50, v[64:65], off nt
	global_load_dword v51, v[66:67], off
	s_add_u32 s10, s10, 64
	s_addc_u32 s11, s11, 0
	v_add_u32_e32 v52, 0x400, v35
	v_lshl_add_u64 v[4:5], v[4:5], 0, s[16:17]
	v_lshl_add_u64 v[8:9], v[8:9], 0, s[16:17]
	v_lshl_add_u64 v[12:13], v[12:13], 0, s[16:17]
	v_lshl_add_u64 v[16:17], v[16:17], 0, s[16:17]
	v_lshl_add_u64 v[20:21], v[20:21], 0, s[16:17]
	v_lshl_add_u64 v[24:25], v[24:25], 0, s[16:17]
	v_lshl_add_u64 v[28:29], v[28:29], 0, s[16:17]
	v_lshl_add_u64 v[30:31], v[30:31], 0, s[16:17]
	s_cmpk_lg_i32 s10, 0x100
	s_waitcnt vmcnt(14)
	v_mul_f32_e32 v36, v36, v37
	s_waitcnt vmcnt(12)
	v_mul_f32_e32 v37, v38, v39
	s_waitcnt vmcnt(10)
	v_mul_f32_e32 v38, v40, v41
	s_waitcnt vmcnt(8)
	v_mul_f32_e32 v39, v42, v43
	s_waitcnt vmcnt(6)
	v_mul_f32_e32 v40, v44, v45
	s_waitcnt vmcnt(4)
	v_mul_f32_e32 v41, v46, v47
	s_waitcnt vmcnt(2)
	v_mul_f32_e32 v42, v48, v49
	s_waitcnt vmcnt(0)
	v_mul_f32_e32 v43, v50, v51
	ds_write2_b32 v35, v36, v37 offset1:66
	ds_write2_b32 v35, v38, v39 offset0:132 offset1:198
	ds_write2_b32 v52, v40, v41 offset0:8 offset1:74
	ds_write2_b32 v52, v42, v43 offset0:140 offset1:206
	v_add_u32_e32 v35, 0x840, v35
	s_cbranch_scc1 .LBB0_352
	v_lshlrev_b32_e32 v0, 3, v34
	v_ashrrev_i32_e32 v24, 3, v34
	v_and_b32_e32 v0, 56, v0
	v_mul_u32_u24_e32 v2, 0x84, v0
	v_lshlrev_b32_e32 v3, 2, v24
	v_readlane_b32 s11, v254, 15
	s_and_b32 s2, 0xffff, s2
	s_and_b32 s10, 0xffff, s3
	s_bfe_u32 s37, s10, 0x10005
	s_bfe_u32 s3, s10, 0x20006
	s_and_b32 s10, s10, 0xffffff00
	s_lshl_b32 s37, s37, 7
	s_lshl_b32 s3, s3, 5
	s_or_b32 s10, s10, s37
	s_or_b32 s10, s10, s3
	v_add3_u32 v28, s11, v2, v3
	ds_read2_b32 v[6:7], v28 offset0:33 offset1:41
	ds_read2_b32 v[8:9], v28 offset1:8
	ds_read2_b32 v[10:11], v28 offset0:66 offset1:74
	ds_read2_b32 v[12:13], v28 offset0:99 offset1:107
	ds_read2_b32 v[14:15], v28 offset0:132 offset1:140
	ds_read2_b32 v[16:17], v28 offset0:165 offset1:173
	ds_read2_b32 v[18:19], v28 offset0:198 offset1:206
	ds_read2_b32 v[20:21], v28 offset0:231 offset1:239
	s_lshl_b32 s2, s2, 1
	s_add_u32 s2, s20, s2
	v_add_u32_e32 v24, s10, v24
	s_addc_u32 s3, s21, 0
	v_lshlrev_b32_e32 v0, 1, v0
	v_ashrrev_i32_e32 v25, 31, v24
	v_lshl_add_u64 v[22:23], s[2:3], 0, v[0:1]
	v_lshlrev_b64 v[26:27], 11, v[24:25]
	s_waitcnt lgkmcnt(6)
	v_cvt_pk_bf16_f32 v2, v8, v6
	s_waitcnt lgkmcnt(4)
	v_cvt_pk_bf16_f32 v3, v10, v12
	s_waitcnt lgkmcnt(2)
	v_cvt_pk_bf16_f32 v4, v14, v16
	s_waitcnt lgkmcnt(0)
	v_cvt_pk_bf16_f32 v5, v18, v20
	v_lshl_add_u64 v[26:27], v[22:23], 0, v[26:27]
	v_add_u32_e32 v6, 8, v24
	global_store_dwordx4 v[26:27], v[2:5], off
	s_nop 1
	v_cvt_pk_bf16_f32 v2, v9, v7
	v_ashrrev_i32_e32 v7, 31, v6
	v_cvt_pk_bf16_f32 v3, v11, v13
	v_cvt_pk_bf16_f32 v4, v15, v17
	v_cvt_pk_bf16_f32 v5, v19, v21
	v_lshlrev_b64 v[6:7], 11, v[6:7]
	ds_read2_b32 v[8:9], v28 offset0:49 offset1:57
	ds_read2_b32 v[10:11], v28 offset0:16 offset1:24
	ds_read2_b32 v[12:13], v28 offset0:82 offset1:90
	ds_read2_b32 v[14:15], v28 offset0:115 offset1:123
	ds_read2_b32 v[16:17], v28 offset0:148 offset1:156
	ds_read2_b32 v[18:19], v28 offset0:181 offset1:189
	ds_read2_b32 v[20:21], v28 offset0:214 offset1:222
	ds_read2_b32 v[26:27], v28 offset0:247 offset1:255
	v_lshl_add_u64 v[6:7], v[22:23], 0, v[6:7]
	global_store_dwordx4 v[6:7], v[2:5], off
	v_add_u32_e32 v6, 16, v24
	v_ashrrev_i32_e32 v7, 31, v6
	v_lshlrev_b64 v[6:7], 11, v[6:7]
	s_waitcnt lgkmcnt(6)
	v_cvt_pk_bf16_f32 v2, v10, v8
	s_waitcnt lgkmcnt(4)
	v_cvt_pk_bf16_f32 v3, v12, v14
	s_waitcnt lgkmcnt(2)
	v_cvt_pk_bf16_f32 v4, v16, v18
	s_waitcnt lgkmcnt(0)
	v_cvt_pk_bf16_f32 v5, v20, v26
	v_lshl_add_u64 v[6:7], v[22:23], 0, v[6:7]
	global_store_dwordx4 v[6:7], v[2:5], off
	v_add_u32_e32 v6, 24, v24
	v_ashrrev_i32_e32 v7, 31, v6
	v_lshlrev_b64 v[6:7], 11, v[6:7]
	v_cvt_pk_bf16_f32 v2, v11, v9
	v_cvt_pk_bf16_f32 v3, v13, v15
	v_cvt_pk_bf16_f32 v4, v17, v19
	v_cvt_pk_bf16_f32 v5, v21, v27
	v_lshl_add_u64 v[6:7], v[22:23], 0, v[6:7]
	global_store_dwordx4 v[6:7], v[2:5], off

; __device__ __forceinline__ void transpose_item(const float* W, int K, int N, bf16_t* WT, const float* gain, int mode, LAS float* scr, int item, int lane) {
;     ...
;     const int nblk = N / 32, kb = item / nblk, nb = item % nblk, k0 = 64 * kb, n0 = 32 * nb;
; #pragma unroll 8
;     for (int i = 0; i < 32; ++i) { const int kk = 2 * i + (lane >> 5); float w = __builtin_nontemporal_load(W + (size_t)(k0 + kk) * N + n0 + (lane & 31)); if (gain) w *= gain[k0 + kk]; scr[kk * 33 + (lane & 31)] = w; }
;     int d0 = n0;
.LBB0_360:
	s_andn2_b64 vcc, exec, s[2:3]
	s_cbranch_vccnz .LBB0_303
	v_readlane_b32 s10, v255, 5
	v_readlane_b32 s11, v255, 6
	s_load_dwordx2 s[2:3], s[10:11], 0x10
	s_load_dwordx2 s[38:39], s[10:11], 0x28
	s_mul_hi_i32 s10, s36, 0x38e38e39
	s_lshr_b32 s11, s10, 31
	s_ashr_i32 s10, s10, 4
	s_add_i32 s10, s10, s11
	s_mul_i32 s11, s10, 0x48
	s_sub_i32 s11, s36, s11
	s_waitcnt lgkmcnt(0)
	s_lshl_b32 s16, s10, 6
	s_lshl_b32 s10, s11, 5
	s_ashr_i32 s11, s10, 31
	s_lshl_b64 s[40:41], s[10:11], 2
	v_mov_b32_e32 v8, v232
	s_add_u32 s18, s38, s40
	s_addc_u32 s19, s39, s41
	v_lshlrev_b32_e32 v0, 2, v8
	v_ashrrev_i32_e32 v4, 5, v8
	v_and_b32_e32 v0, 0x7c, v0
	s_cmp_lg_u64 s[2:3], 0
	v_lshl_add_u64 v[2:3], s[18:19], 0, v[0:1]
	s_cselect_b64 s[18:19], -1, 0
	s_ashr_i32 s17, s16, 31
	v_ashrrev_i32_e32 v5, 31, v4
	s_movk_i32 s11, 0x84
	v_lshl_add_u64 v[6:7], v[4:5], 0, s[16:17]
	v_mul_lo_u32 v5, v4, s11
	v_readlane_b32 s11, v254, 15
	v_add_u32_e32 v10, s16, v4
	s_nop 0
	v_add3_u32 v9, v5, v0, s11
	v_mov_b64_e32 v[4:5], s[40:41]
	v_mad_u64_u32 v[4:5], s[40:41], v6, s91, v[4:5]
	v_mad_i32_i24 v5, v7, s91, v5
	v_or_b32_e32 v4, v4, v0
	v_lshl_add_u64 v[6:7], v[6:7], 2, s[2:3]
	v_lshl_add_u64 v[4:5], s[38:39], 0, v[4:5]
	v_lshl_add_u64 v[6:7], v[6:7], 0, 56
	s_bfe_u32 s11, s10, 0x10005
	s_bfe_u32 s3, s10, 0x20006
	s_and_b32 s10, s10, 0xffffff00
	s_lshl_b32 s11, s11, 7
	s_lshl_b32 s3, s3, 5
	s_or_b32 s10, s10, s11
	s_or_b32 s10, s10, s3
	s_mov_b32 s2, 0
	s_branch .LBB0_363
